# v71 + rstd_setup split in two passes (up and in GEMM phases): the unit scan only issues the ssq loads (one register set per distinct row panel), reduce/rsqrt/ds_write run once at the end of the GEMM p
# baseline (speedup 1.0000x reference)
.LBB0_162:
	s_cmp_ge_i32 s31, s68
	s_cselect_b64 s[0:1], -1, 0
	s_cmp_lt_i32 s31, s69
	s_cselect_b64 s[18:19], -1, 0
	s_and_b64 s[0:1], s[0:1], s[18:19]
	s_andn2_b64 vcc, exec, s[0:1]
	s_cbranch_vccnz .LBB0_187
	s_waitcnt lgkmcnt(0)
	v_mov_b32_e32 v1, v222
	v_readlane_b32 s18, v253, 51
	v_ashrrev_i32_e32 v0, 1, v1
	v_and_b32_e32 v1, 1, v1
	v_lshlrev_b32_e32 v2, 1, v1
	v_cmp_eq_u32_e64 s[44:45], 0, v1
	v_lshl_add_u32 v1, v0, 2, s18
	s_mov_b32 s47, -1
	v_lshlrev_b32_e32 v152, 4, v2
	s_mov_b64 s[18:19], s[2:3]
	s_mov_b32 s85, 0
	s_branch .LBB0_167

.LBB0_167:
	v_cmp_gt_i64_e32 vcc, s[18:19], v[158:159]
	s_mov_b64 s[20:21], -1
	s_cbranch_vccnz .LBB0_166
	s_ashr_i32 s20, s18, 31
	s_lshr_b32 s20, s20, 29
	s_add_i32 s20, s18, s20
	s_ashr_i32 s21, s20, 3
	s_and_b32 s20, s20, -8
	s_sub_i32 s20, s18, s20
	s_cmp_lt_i32 s20, 0
	s_cselect_b32 s46, s36, 0x160
	s_mul_i32 s20, s20, s46
	s_add_i32 s20, s20, s21
	s_mul_hi_i32 s21, s20, 0x2e8ba2e9
	s_lshr_b32 s46, s21, 31
	s_ashr_i32 s21, s21, 5
	s_add_i32 s21, s21, s46
	s_lshl_b32 s46, s21, 3
	s_sub_i32 s48, 0x80, s46
	s_min_i32 s48, s48, 8
	s_mulk_i32 s21, 0xb0
	s_sub_i32 s20, s20, s21
	s_and_b32 s20, s20, 7
	s_add_i32 s46, s46, s20
	s_cmp_eq_u32 s46, s47
	s_cbranch_scc1 .LBB0_165
	v_lshl_add_u32 v2, s46, 8, v0
	s_waitcnt lgkmcnt(0)
	v_ashrrev_i32_e32 v3, 31, v2
	v_lshlrev_b64 v[2:3], 6, v[2:3]
	v_lshl_add_u64 v[2:3], s[28:29], 0, v[2:3]
	v_lshl_add_u64 v[6:7], v[2:3], 0, v[152:153]
	s_cmp_lt_u32 s85, 3
	s_cbranch_scc0 .Lmy_rsu_inl
	s_cmp_eq_u32 s85, 0
	s_cbranch_scc0 .Lmy_rsu_0
	global_load_dwordx4 v[20:23], v[6:7], off
	s_nop 0
	global_load_dwordx4 v[24:27], v[6:7], off offset:16
	s_mov_b32 s82, s46
	s_branch .Lmy_rsu_d
.Lmy_rsu_0:
	s_cmp_eq_u32 s85, 1
	s_cbranch_scc0 .Lmy_rsu_1
	global_load_dwordx4 v[28:31], v[6:7], off
	s_nop 0
	global_load_dwordx4 v[32:35], v[6:7], off offset:16
	s_mov_b32 s83, s46
	s_branch .Lmy_rsu_d
.Lmy_rsu_1:
	global_load_dwordx4 v[36:39], v[6:7], off
	s_nop 0
	global_load_dwordx4 v[40:43], v[6:7], off offset:16
	s_mov_b32 s84, s46
.Lmy_rsu_d:
	s_add_i32 s85, s85, 1
	s_mov_b32 s47, s46
	s_branch .LBB0_165
.Lmy_rsu_inl:
	global_load_dwordx4 v[2:5], v[6:7], off
	s_nop 0
	global_load_dwordx4 v[6:9], v[6:7], off offset:16
	v_cmp_lt_i32_e32 vcc, v206, v205
	s_waitcnt vmcnt(0)
	v_pk_add_f32 v[4:5], v[4:5], v[8:9]
	v_pk_add_f32 v[2:3], v[2:3], v[6:7]
	s_nop 0
	v_add_f32_e32 v2, v2, v3
	v_add_f32_e32 v3, v4, v5
	v_add_f32_e32 v2, v2, v3
	v_cndmask_b32_e32 v3, v204, v206, vcc
	v_lshlrev_b32_e32 v3, 2, v3
	ds_bpermute_b32 v3, v3, v2
	s_and_saveexec_b64 s[20:21], s[44:45]
	s_cbranch_execz .LBB0_164
	s_waitcnt lgkmcnt(0)
	v_add_f32_e32 v2, v2, v3
	v_fmamk_f32 v2, v2, 0x3a800000, v202
	s_mov_b32 s47, 0x800000
	v_cmp_gt_f32_e32 vcc, s47, v2
	v_mul_f32_e32 v3, 0x4b800000, v2
	s_lshl_b32 s47, s46, 7
	v_cndmask_b32_e32 v2, v2, v3, vcc
	v_rsq_f32_e32 v2, v2
	s_and_b32 s47, s47, 0xc00
	v_mul_f32_e32 v3, 0x45800000, v2
	v_cndmask_b32_e32 v2, v2, v3, vcc
	v_add_u32_e32 v3, s47, v1
	ds_write_b32 v3, v2
	s_branch .LBB0_164

.LBB0_174:
	v_and_b32_e32 v144, 15, v10
	v_lshrrev_b32_e32 v10, 1, v10
	v_readlane_b32 s62, v254, 6
	v_and_b32_e32 v10, 24, v10
	s_lshl_b32 s18, s18, 5
	v_mov_b32_e32 v133, v153
	v_readlane_b32 s63, v254, 7
	v_lshlrev_b32_e32 v11, 1, v10
	v_lshlrev_b32_e32 v16, 2, v144
	s_and_b32 s21, s18, 0x60
	s_add_i32 m0, s68, 0x18000
	v_lshl_add_u64 v[0:1], v[0:1], 0, s[22:23]
	v_lshl_add_u64 v[12:13], s[62:63], 0, v[132:133]
	v_mov_b32_e32 v131, v153
	s_lshl_b32 s76, s19, 6
	v_lshl_or_b32 v11, v144, 6, v11
	s_lshl_b32 s19, s19, 13
	v_and_b32_e32 v17, 32, v16
	s_lshl_b32 s18, s21, 7
	global_load_lds_dwordx4 v[0:1], off
	v_lshl_add_u64 v[0:1], v[2:3], 0, s[22:23]
	s_add_i32 m0, s68, 0x1a000
	s_add_i32 s77, s68, 0x8000
	s_add_i32 s78, s68, 0xa000
	v_lshl_add_u64 v[14:15], s[62:63], 0, v[130:131]
	v_bitop3_b32 v145, v11, s18, v17 bitop3:0xde
	global_load_lds_dwordx4 v[0:1], off
	v_lshl_add_u64 v[0:1], v[12:13], 0, s[22:23]
	s_mov_b32 m0, s77
	s_add_u32 s18, s60, 0x40080
	v_bitop3_b32 v18, v11, s19, v17 bitop3:0xde
	global_load_lds_dwordx4 v[0:1], off
	v_lshl_add_u64 v[0:1], v[14:15], 0, s[22:23]
	s_mov_b32 m0, s78
	s_addc_u32 s19, s61, 0
	global_load_lds_dwordx4 v[0:1], off
	s_add_i32 m0, s68, 0x1c000
	v_lshl_add_u64 v[0:1], s[18:19], 0, v[152:153]
	global_load_lds_dwordx4 v[0:1], off
	v_lshl_add_u64 v[0:1], s[18:19], 0, v[128:129]
	s_add_i32 m0, s68, 0x1e000
	s_cmpk_lt_u32 s20, 0x100
	global_load_lds_dwordx4 v[0:1], off
	s_waitcnt vmcnt(8)
	s_barrier
	v_lshlrev_b32_e32 v0, 14, v4
	v_and_b32_e32 v0, 0xffff8000, v0
	v_lshl_add_u32 v0, v5, 11, v0
	v_and_b32_e32 v1, 1, v4
	v_lshl_or_b32 v0, v1, 6, v0
	s_cselect_b64 s[18:19], -1, 0
	s_and_b32 s20, s20, 0xffffff00
	v_lshl_add_u32 v134, v6, 1, v0
	v_lshlrev_b32_e32 v0, 14, v8
	s_add_i32 s20, s20, 0
	v_and_b32_e32 v0, 0xffff8000, v0
	s_waitcnt vmcnt(6)
	s_add_i32 s20, s20, 0x20400
	v_lshl_add_u32 v0, v7, 11, v0
	v_and_b32_e32 v1, 1, v8
	v_add_u32_e32 v146, s20, v16
	v_or_b32_e32 v147, s21, v10
	v_lshl_or_b32 v0, v1, 6, v0
	v_readlane_b32 s20, v253, 16
	v_mov_b32_e32 v135, v153
	v_lshl_add_u32 v136, v9, 1, v0
	v_mov_b32_e32 v137, v153
	s_mov_b32 s79, 0
	v_add_u32_e32 v148, 0, v18
	v_readlane_b32 s80, v253, 15
	s_mov_b32 s81, s20
	s_barrier
	v_readlane_b32 s21, v253, 17
	s_cmp_eq_u32 s85, 0
	s_cbranch_scc1 .Lmy_rsu_p2d
	v_readlane_b32 s89, v253, 51
	v_and_b32_e32 v44, 1, v222
	v_ashrrev_i32_e32 v45, 1, v222
	s_nop 0
	v_lshl_add_u32 v45, v45, 2, s89
	v_pk_add_f32 v[22:23], v[22:23], v[26:27]
	v_pk_add_f32 v[20:21], v[20:21], v[24:25]
	v_cmp_lt_i32_e32 vcc, v206, v205
	v_add_f32_e32 v20, v20, v21
	v_add_f32_e32 v21, v22, v23
	v_add_f32_e32 v20, v20, v21
	v_cndmask_b32_e32 v21, v204, v206, vcc
	v_lshlrev_b32_e32 v21, 2, v21
	ds_bpermute_b32 v21, v21, v20
	v_cmp_eq_u32_e32 vcc, 0, v44
	s_and_saveexec_b64 s[86:87], vcc
	s_waitcnt lgkmcnt(0)
	v_add_f32_e32 v20, v20, v21
	v_fmamk_f32 v20, v20, 0x3a800000, v202
	v_cmp_gt_f32_e32 vcc, 0x800000, v20
	v_mul_f32_e32 v21, 0x4b800000, v20
	v_mov_b32_e32 v46, s82
	v_lshlrev_b32_e32 v46, 7, v46
	v_cndmask_b32_e32 v20, v20, v21, vcc
	v_rsq_f32_e32 v20, v20
	v_and_b32_e32 v46, 0xc00, v46
	v_mul_f32_e32 v21, 0x45800000, v20
	v_add_u32_e32 v46, v46, v45
	v_cndmask_b32_e32 v20, v20, v21, vcc
	ds_write_b32 v46, v20
	s_or_b64 exec, exec, s[86:87]
	s_cmp_lt_u32 s85, 2
	s_cbranch_scc1 .Lmy_rsu_p2d
	v_pk_add_f32 v[30:31], v[30:31], v[34:35]
	v_pk_add_f32 v[28:29], v[28:29], v[32:33]
	v_cmp_lt_i32_e32 vcc, v206, v205
	v_add_f32_e32 v28, v28, v29
	v_add_f32_e32 v29, v30, v31
	v_add_f32_e32 v28, v28, v29
	v_cndmask_b32_e32 v29, v204, v206, vcc
	v_lshlrev_b32_e32 v29, 2, v29
	ds_bpermute_b32 v29, v29, v28
	v_cmp_eq_u32_e32 vcc, 0, v44
	s_and_saveexec_b64 s[86:87], vcc
	s_waitcnt lgkmcnt(0)
	v_add_f32_e32 v28, v28, v29
	v_fmamk_f32 v28, v28, 0x3a800000, v202
	v_cmp_gt_f32_e32 vcc, 0x800000, v28
	v_mul_f32_e32 v29, 0x4b800000, v28
	v_mov_b32_e32 v46, s83
	v_lshlrev_b32_e32 v46, 7, v46
	v_cndmask_b32_e32 v28, v28, v29, vcc
	v_rsq_f32_e32 v28, v28
	v_and_b32_e32 v46, 0xc00, v46
	v_mul_f32_e32 v29, 0x45800000, v28
	v_add_u32_e32 v46, v46, v45
	v_cndmask_b32_e32 v28, v28, v29, vcc
	ds_write_b32 v46, v28
	s_or_b64 exec, exec, s[86:87]
	s_cmp_lt_u32 s85, 3
	s_cbranch_scc1 .Lmy_rsu_p2d
	v_pk_add_f32 v[38:39], v[38:39], v[42:43]
	v_pk_add_f32 v[36:37], v[36:37], v[40:41]
	v_cmp_lt_i32_e32 vcc, v206, v205
	v_add_f32_e32 v36, v36, v37
	v_add_f32_e32 v37, v38, v39
	v_add_f32_e32 v36, v36, v37
	v_cndmask_b32_e32 v37, v204, v206, vcc
	v_lshlrev_b32_e32 v37, 2, v37
	ds_bpermute_b32 v37, v37, v36
	v_cmp_eq_u32_e32 vcc, 0, v44
	s_and_saveexec_b64 s[86:87], vcc
	s_waitcnt lgkmcnt(0)
	v_add_f32_e32 v36, v36, v37
	v_fmamk_f32 v36, v36, 0x3a800000, v202
	v_cmp_gt_f32_e32 vcc, 0x800000, v36
	v_mul_f32_e32 v37, 0x4b800000, v36
	v_mov_b32_e32 v46, s84
	v_lshlrev_b32_e32 v46, 7, v46
	v_cndmask_b32_e32 v36, v36, v37, vcc
	v_rsq_f32_e32 v36, v36
	v_and_b32_e32 v46, 0xc00, v46
	v_mul_f32_e32 v37, 0x45800000, v36
	v_add_u32_e32 v46, v46, v45
	v_cndmask_b32_e32 v36, v36, v37, vcc
	ds_write_b32 v46, v36
	s_or_b64 exec, exec, s[86:87]
.Lmy_rsu_p2d:
	s_waitcnt lgkmcnt(0)
	s_branch .LBB0_177
.LBB0_175:
	s_mov_b64 s[44:45], 0

.LBB0_400:
	v_readlane_b32 s0, v250, 2
	v_readlane_b32 s1, v250, 3
	s_andn2_b64 vcc, exec, s[0:1]
	s_cbranch_vccnz .LBB0_160
	s_cmp_ge_i32 s8, s68
	s_cselect_b64 s[0:1], -1, 0
	s_and_b64 s[0:1], s[0:1], s[10:11]
	s_andn2_b64 vcc, exec, s[0:1]
	s_cbranch_vccnz .LBB0_466
	v_mov_b32_e32 v4, v222
	v_readlane_b32 s10, v253, 62
	v_lshlrev_b32_e32 v0, 2, v4
	s_waitcnt lgkmcnt(0)
	v_ashrrev_i32_e32 v1, 31, v0
	v_readlane_b32 s11, v253, 63
	v_lshl_add_u32 v4, v4, 4, 0
	v_mov_b32_e32 v5, v222
	v_lshl_add_u64 v[0:1], v[0:1], 2, s[10:11]
	global_load_dwordx4 v[0:3], v[0:1], off
	v_add_u32_e32 v4, 0x21400, v4
	v_readlane_b32 s8, v253, 51
	s_mov_b32 s18, -1
	s_mov_b64 s[10:11], s[2:3]
	s_waitcnt vmcnt(0)
	ds_write_b128 v4, v[0:3]
	s_nop 0
	v_and_b32_e32 v1, 1, v5
	v_ashrrev_i32_e32 v0, 1, v5
	v_lshlrev_b32_e32 v2, 1, v1
	v_cmp_eq_u32_e64 s[46:47], 0, v1
	v_lshl_add_u32 v1, v0, 2, s8
	v_lshlrev_b32_e32 v152, 4, v2
	s_mov_b32 s85, 0
	s_branch .LBB0_406

.LBB0_406:
	v_cmp_gt_i64_e32 vcc, s[10:11], v[166:167]
	s_mov_b64 s[16:17], -1
	s_cbranch_vccnz .LBB0_405
	s_ashr_i32 s8, s10, 31
	s_lshr_b32 s8, s8, 29
	s_add_i32 s8, s10, s8
	s_ashr_i32 s16, s8, 3
	s_and_b32 s8, s8, -8
	s_sub_i32 s8, s10, s8
	s_cmp_lt_i32 s8, 0
	s_movk_i32 s17, 0xd1
	s_cselect_b32 s17, s17, 0xd0
	s_mul_i32 s8, s8, s17
	s_add_i32 s8, s8, s16
	s_mul_hi_i32 s16, s8, 0x4ec4ec4f
	s_lshr_b32 s17, s16, 31
	s_ashr_i32 s16, s16, 5
	s_add_i32 s16, s16, s17
	s_lshl_b32 s17, s16, 3
	s_sub_i32 s19, 0x80, s17
	s_min_i32 s19, s19, 8
	s_mulk_i32 s16, 0x68
	s_sub_i32 s8, s8, s16
	s_and_b32 s8, s8, 7
	s_add_i32 s8, s17, s8
	s_cmp_eq_u32 s8, s18
	s_cbranch_scc1 .LBB0_404
	v_lshl_add_u32 v2, s8, 8, v0
	s_waitcnt lgkmcnt(0)
	v_ashrrev_i32_e32 v3, 31, v2
	v_lshlrev_b64 v[2:3], 6, v[2:3]
	v_lshl_add_u64 v[2:3], s[28:29], 0, v[2:3]
	v_lshl_add_u64 v[6:7], v[2:3], 0, v[152:153]
	s_cmp_lt_u32 s85, 3
	s_cbranch_scc0 .Lmy_rsi_inl
	s_cmp_eq_u32 s85, 0
	s_cbranch_scc0 .Lmy_rsi_0
	global_load_dwordx4 v[20:23], v[6:7], off
	s_nop 0
	global_load_dwordx4 v[24:27], v[6:7], off offset:16
	s_mov_b32 s82, s8
	s_branch .Lmy_rsi_d
.Lmy_rsi_0:
	s_cmp_eq_u32 s85, 1
	s_cbranch_scc0 .Lmy_rsi_1
	global_load_dwordx4 v[28:31], v[6:7], off
	s_nop 0
	global_load_dwordx4 v[32:35], v[6:7], off offset:16
	s_mov_b32 s83, s8
	s_branch .Lmy_rsi_d
.Lmy_rsi_1:
	global_load_dwordx4 v[36:39], v[6:7], off
	s_nop 0
	global_load_dwordx4 v[40:43], v[6:7], off offset:16
	s_mov_b32 s84, s8
.Lmy_rsi_d:
	s_add_i32 s85, s85, 1
	s_mov_b32 s18, s8
	s_branch .LBB0_404
.Lmy_rsi_inl:
	global_load_dwordx4 v[2:5], v[6:7], off
	s_nop 0
	global_load_dwordx4 v[6:9], v[6:7], off offset:16
	v_cmp_lt_i32_e32 vcc, v206, v205
	s_waitcnt vmcnt(0)
	v_pk_add_f32 v[4:5], v[4:5], v[8:9]
	v_pk_add_f32 v[2:3], v[2:3], v[6:7]
	s_nop 0
	v_add_f32_e32 v2, v2, v3
	v_add_f32_e32 v3, v4, v5
	v_add_f32_e32 v2, v2, v3
	v_cndmask_b32_e32 v3, v204, v206, vcc
	v_lshlrev_b32_e32 v3, 2, v3
	ds_bpermute_b32 v3, v3, v2
	s_and_saveexec_b64 s[16:17], s[46:47]
	s_cbranch_execz .LBB0_403
	s_waitcnt lgkmcnt(0)
	v_add_f32_e32 v2, v2, v3
	v_fmamk_f32 v2, v2, 0x3a800000, v202
	s_mov_b32 s18, 0x800000
	v_cmp_gt_f32_e32 vcc, s18, v2
	v_mul_f32_e32 v3, 0x4b800000, v2
	s_lshl_b32 s18, s8, 7
	v_cndmask_b32_e32 v2, v2, v3, vcc
	v_rsq_f32_e32 v2, v2
	s_and_b32 s18, s18, 0xc00
	v_mul_f32_e32 v3, 0x45800000, v2
	v_cndmask_b32_e32 v2, v2, v3, vcc
	v_add_u32_e32 v3, s18, v1
	ds_write_b32 v3, v2
	s_branch .LBB0_403

.LBB0_413:
	v_and_b32_e32 v7, 15, v6
	v_lshrrev_b32_e32 v6, 1, v6
	v_readlane_b32 s48, v254, 50
	v_and_b32_e32 v16, 24, v6
	s_lshl_b32 s16, s16, 5
	v_readlane_b32 s49, v254, 51
	v_lshlrev_b32_e32 v6, 1, v16
	v_lshlrev_b32_e32 v17, 2, v7
	s_and_b32 s19, s16, 0x60
	v_lshl_add_u64 v[8:9], s[48:49], 0, v[152:153]
	v_mov_b32_e32 v145, v153
	v_readlane_b32 s44, v254, 46
	v_lshl_or_b32 v184, s17, 6, v7
	v_lshl_or_b32 v6, v7, 6, v6
	s_lshl_b32 s17, s17, 13
	v_and_b32_e32 v7, 32, v17
	s_lshl_b32 s16, s19, 7
	v_lshl_add_u64 v[10:11], s[48:49], 0, v[144:145]
	v_mov_b32_e32 v149, v153
	v_readlane_b32 s45, v254, 47
	v_bitop3_b32 v18, v6, s17, v7 bitop3:0xde
	v_bitop3_b32 v185, v6, s16, v7 bitop3:0xde
	s_add_i32 m0, s59, 0x18000
	v_lshl_add_u64 v[6:7], v[8:9], 0, s[22:23]
	v_lshl_add_u64 v[12:13], s[44:45], 0, v[148:149]
	v_mov_b32_e32 v147, v153
	global_load_lds_dwordx4 v[6:7], off
	v_lshl_add_u64 v[6:7], v[10:11], 0, s[22:23]
	s_add_i32 m0, s59, 0x1a000
	s_add_i32 s69, s59, 0x8000
	v_lshl_add_u64 v[14:15], s[44:45], 0, v[146:147]
	global_load_lds_dwordx4 v[6:7], off
	v_lshl_add_u64 v[6:7], v[12:13], 0, s[22:23]
	s_mov_b32 m0, s69
	s_add_i32 s74, s59, 0xa000
	v_readlane_b32 s16, v254, 52
	global_load_lds_dwordx4 v[6:7], off
	v_lshl_add_u64 v[6:7], v[14:15], 0, s[22:23]
	s_mov_b32 m0, s74
	v_readlane_b32 s17, v254, 53
	global_load_lds_dwordx4 v[6:7], off
	s_add_i32 m0, s59, 0x1c000
	v_lshl_add_u64 v[6:7], s[16:17], 0, v[152:153]
	global_load_lds_dwordx4 v[6:7], off
	v_lshl_add_u64 v[6:7], s[16:17], 0, v[144:145]
	s_add_i32 m0, s59, 0x1e000
	s_cmpk_lt_u32 s18, 0x100
	global_load_lds_dwordx4 v[6:7], off
	s_waitcnt vmcnt(8)
	s_barrier
	v_lshlrev_b32_e32 v6, 14, v0
	v_and_b32_e32 v6, 0xffff8000, v6
	v_lshl_add_u32 v1, v1, 11, v6
	v_and_b32_e32 v0, 1, v0
	v_lshl_or_b32 v0, v0, 6, v1
	s_cselect_b64 s[16:17], -1, 0
	s_and_b32 s18, s18, 0xffffff00
	v_lshl_add_u32 v150, v2, 1, v0
	v_lshlrev_b32_e32 v0, 14, v4
	s_add_i32 s18, s18, 0
	v_and_b32_e32 v0, 0xffff8000, v0
	s_waitcnt vmcnt(6)
	s_add_i32 s18, s18, 0x20400
	v_lshl_add_u32 v0, v3, 11, v0
	v_and_b32_e32 v1, 1, v4
	v_add_u32_e32 v186, s18, v17
	v_or_b32_e32 v187, s19, v16
	v_lshl_or_b32 v0, v1, 6, v0
	v_readlane_b32 s18, v253, 30
	v_mov_b32_e32 v151, v153
	v_lshl_add_u32 v172, v5, 1, v0
	v_mov_b32_e32 v173, v153
	s_mov_b32 s75, 0
	v_add_u32_e32 v188, 0, v18
	v_readlane_b32 s77, v253, 23
	s_mov_b32 s76, s18
	s_barrier
	v_readlane_b32 s19, v253, 31
	s_cmp_eq_u32 s85, 0
	s_cbranch_scc1 .Lmy_rsi_p2d
	v_readlane_b32 s89, v253, 51
	v_and_b32_e32 v44, 1, v222
	v_ashrrev_i32_e32 v45, 1, v222
	s_nop 0
	v_lshl_add_u32 v45, v45, 2, s89
	v_pk_add_f32 v[22:23], v[22:23], v[26:27]
	v_pk_add_f32 v[20:21], v[20:21], v[24:25]
	v_cmp_lt_i32_e32 vcc, v206, v205
	v_add_f32_e32 v20, v20, v21
	v_add_f32_e32 v21, v22, v23
	v_add_f32_e32 v20, v20, v21
	v_cndmask_b32_e32 v21, v204, v206, vcc
	v_lshlrev_b32_e32 v21, 2, v21
	ds_bpermute_b32 v21, v21, v20
	v_cmp_eq_u32_e32 vcc, 0, v44
	s_and_saveexec_b64 s[86:87], vcc
	s_waitcnt lgkmcnt(0)
	v_add_f32_e32 v20, v20, v21
	v_fmamk_f32 v20, v20, 0x3a800000, v202
	v_cmp_gt_f32_e32 vcc, 0x800000, v20
	v_mul_f32_e32 v21, 0x4b800000, v20
	v_mov_b32_e32 v46, s82
	v_lshlrev_b32_e32 v46, 7, v46
	v_cndmask_b32_e32 v20, v20, v21, vcc
	v_rsq_f32_e32 v20, v20
	v_and_b32_e32 v46, 0xc00, v46
	v_mul_f32_e32 v21, 0x45800000, v20
	v_add_u32_e32 v46, v46, v45
	v_cndmask_b32_e32 v20, v20, v21, vcc
	ds_write_b32 v46, v20
	s_or_b64 exec, exec, s[86:87]
	s_cmp_lt_u32 s85, 2
	s_cbranch_scc1 .Lmy_rsi_p2d
	v_pk_add_f32 v[30:31], v[30:31], v[34:35]
	v_pk_add_f32 v[28:29], v[28:29], v[32:33]
	v_cmp_lt_i32_e32 vcc, v206, v205
	v_add_f32_e32 v28, v28, v29
	v_add_f32_e32 v29, v30, v31
	v_add_f32_e32 v28, v28, v29
	v_cndmask_b32_e32 v29, v204, v206, vcc
	v_lshlrev_b32_e32 v29, 2, v29
	ds_bpermute_b32 v29, v29, v28
	v_cmp_eq_u32_e32 vcc, 0, v44
	s_and_saveexec_b64 s[86:87], vcc
	s_waitcnt lgkmcnt(0)
	v_add_f32_e32 v28, v28, v29
	v_fmamk_f32 v28, v28, 0x3a800000, v202
	v_cmp_gt_f32_e32 vcc, 0x800000, v28
	v_mul_f32_e32 v29, 0x4b800000, v28
	v_mov_b32_e32 v46, s83
	v_lshlrev_b32_e32 v46, 7, v46
	v_cndmask_b32_e32 v28, v28, v29, vcc
	v_rsq_f32_e32 v28, v28
	v_and_b32_e32 v46, 0xc00, v46
	v_mul_f32_e32 v29, 0x45800000, v28
	v_add_u32_e32 v46, v46, v45
	v_cndmask_b32_e32 v28, v28, v29, vcc
	ds_write_b32 v46, v28
	s_or_b64 exec, exec, s[86:87]
	s_cmp_lt_u32 s85, 3
	s_cbranch_scc1 .Lmy_rsi_p2d
	v_pk_add_f32 v[38:39], v[38:39], v[42:43]
	v_pk_add_f32 v[36:37], v[36:37], v[40:41]
	v_cmp_lt_i32_e32 vcc, v206, v205
	v_add_f32_e32 v36, v36, v37
	v_add_f32_e32 v37, v38, v39
	v_add_f32_e32 v36, v36, v37
	v_cndmask_b32_e32 v37, v204, v206, vcc
	v_lshlrev_b32_e32 v37, 2, v37
	ds_bpermute_b32 v37, v37, v36
	v_cmp_eq_u32_e32 vcc, 0, v44
	s_and_saveexec_b64 s[86:87], vcc
	s_waitcnt lgkmcnt(0)
	v_add_f32_e32 v36, v36, v37
	v_fmamk_f32 v36, v36, 0x3a800000, v202
	v_cmp_gt_f32_e32 vcc, 0x800000, v36
	v_mul_f32_e32 v37, 0x4b800000, v36
	v_mov_b32_e32 v46, s84
	v_lshlrev_b32_e32 v46, 7, v46
	v_cndmask_b32_e32 v36, v36, v37, vcc
	v_rsq_f32_e32 v36, v36
	v_and_b32_e32 v46, 0xc00, v46
	v_mul_f32_e32 v37, 0x45800000, v36
	v_add_u32_e32 v46, v46, v45
	v_cndmask_b32_e32 v36, v36, v37, vcc
	ds_write_b32 v46, v36
	s_or_b64 exec, exec, s[86:87]
.Lmy_rsi_p2d:
	s_waitcnt lgkmcnt(0)
	s_branch .LBB0_416
.LBB0_414:
	s_mov_b64 s[44:45], 0
